# in-proj epilogue gate tiles: 8-byte gate stores lane-transposed by ds_bpermute (4 neighbouring lanes store one row's 32 bytes)
# baseline (speedup 1.0000x reference)
; __device__ __forceinline__ float sigmoidf_(float x) { return __builtin_amdgcn_rcpf(1.f + __expf(-x)); }
;     __device__ __forceinline__ void operator()(f32x4 (&acc)[2][2][4][2], const pg8::Unit& u, int wr, int wc, int fr, int fq) const {
;     ...
;         if (u.pn >= 28) {
; #pragma unroll
;             for (int ai = 0; ai < 2; ++ai)
; #pragma unroll
;                 for (int m = 0; m < 4; ++m) {
;                     unsigned char* gp = gq + (size_t)(row0 + ai * 128 + m * 16) * 4096 + (u.pn - 28) * 256 + cin;
; #pragma unroll
;                     for (int bj = 0; bj < 2; ++bj) { unsigned w2[2];
; #pragma unroll
;                         for (int n = 0; n < 2; ++n) {
;                             const f32x4 v = acc[ai][bj][m][n];
;                             const unsigned b0 = (unsigned)(sigmoidf_(v[0]) * 255.f + 0.5f), b1 = (unsigned)(sigmoidf_(v[1]) * 255.f + 0.5f),
;                                            b2 = (unsigned)(sigmoidf_(v[2]) * 255.f + 0.5f), b3 = (unsigned)(sigmoidf_(v[3]) * 255.f + 0.5f);
;                             w2[n] = b0 | (b1 << 8) | (b2 << 16) | (b3 << 24);
;                         }
;                         u32x2 o = {w2[0], w2[1]}; *(u32x2*)(gp + bj * 128) = o; }
.LBB0_1065:
	s_and_b64 vcc, exec, s[0:1]
	s_cbranch_vccz .LBB0_1067
	v_readlane_b32 s52, v251, 1
	v_readlane_b32 s53, v251, 2
	v_readlane_b32 s54, v251, 3
	v_readlane_b32 s55, v251, 4
	v_readlane_b32 s56, v251, 5
	v_readlane_b32 s57, v251, 6
	v_readlane_b32 s58, v251, 7
	v_readlane_b32 s59, v251, 8
	v_ashrrev_i32_e32 v155, 31, v154
	s_add_i32 s0, s22, 0xffffe400
	v_lshlrev_b64 v[192:193], 12, v[154:155]
	s_ashr_i32 s1, s0, 31
	v_lshl_add_u64 v[192:193], s[58:59], 0, v[192:193]
	s_mov_b32 s20, 0x437f0000
	s_mov_b32 s21, 0xbfb8aa3b
	v_lshl_add_u64 v[192:193], v[192:193], 0, s[0:1]
	v_lshl_add_u64 v[192:193], v[192:193], 0, v[142:143]
	v_bfe_u32 v212, v198, 2, 4
	v_and_b32_e32 v213, 15, v198
	v_sub_u32_e32 v212, v212, v213
	v_and_b32_e32 v213, 3, v198
	v_bfe_u32 v214, v198, 4, 2
	v_sub_u32_e32 v213, v213, v214
	v_lshlrev_b32_e32 v212, 12, v212
	v_lshl_add_u32 v212, v213, 3, v212
	v_ashrrev_i32_e32 v213, 31, v212
	v_lshl_add_u64 v[192:193], v[192:193], 0, v[212:213]
	v_and_b32_e32 v214, 3, v198
	v_bfe_u32 v215, v198, 2, 4
	v_lshl_add_u32 v214, v214, 4, v215
	v_lshlrev_b32_e32 v214, 2, v214
	v_pk_mul_f32 v[172:173], v[126:127], s[20:21] op_sel:[0,1] op_sel_hi:[1,1]
	v_pk_mul_f32 v[174:175], v[128:129], s[20:21] op_sel:[0,1] op_sel_hi:[1,1]
	v_pk_mul_f32 v[176:177], v[122:123], s[20:21] op_sel:[0,1] op_sel_hi:[1,1]
	v_pk_mul_f32 v[178:179], v[124:125], s[20:21] op_sel:[0,1] op_sel_hi:[1,1]
	v_exp_f32_e32 v172, v172
	v_exp_f32_e32 v173, v173
	v_exp_f32_e32 v174, v174
	v_exp_f32_e32 v175, v175
	v_exp_f32_e32 v176, v176
	v_exp_f32_e32 v177, v177
	v_exp_f32_e32 v178, v178
	v_exp_f32_e32 v179, v179
	v_pk_add_f32 v[172:173], v[172:173], 1.0 op_sel_hi:[1,0]
	v_pk_add_f32 v[174:175], v[174:175], 1.0 op_sel_hi:[1,0]
	v_pk_add_f32 v[176:177], v[176:177], 1.0 op_sel_hi:[1,0]
	v_pk_add_f32 v[178:179], v[178:179], 1.0 op_sel_hi:[1,0]
	v_rcp_f32_e32 v172, v172
	v_rcp_f32_e32 v173, v173
	v_rcp_f32_e32 v174, v174
	v_rcp_f32_e32 v175, v175
	v_rcp_f32_e32 v176, v176
	v_rcp_f32_e32 v177, v177
	v_rcp_f32_e32 v178, v178
	v_rcp_f32_e32 v179, v179
	s_nop 0
	v_pk_fma_f32 v[172:173], v[172:173], s[20:21], 0.5 op_sel_hi:[1,0,0]
	v_pk_fma_f32 v[174:175], v[174:175], s[20:21], 0.5 op_sel_hi:[1,0,0]
	v_pk_fma_f32 v[176:177], v[176:177], s[20:21], 0.5 op_sel_hi:[1,0,0]
	v_pk_fma_f32 v[178:179], v[178:179], s[20:21], 0.5 op_sel_hi:[1,0,0]
	v_max_f32_e32 v172, 1.0, v172
	v_max_f32_e32 v173, 1.0, v173
	v_max_f32_e32 v174, 1.0, v174
	v_max_f32_e32 v175, 1.0, v175
	v_max_f32_e32 v176, 1.0, v176
	v_max_f32_e32 v177, 1.0, v177
	v_max_f32_e32 v178, 1.0, v178
	v_max_f32_e32 v179, 1.0, v179
	v_cvt_u32_f32_e32 v180, v172
	v_cvt_u32_f32_e32 v181, v176
	v_cvt_u32_f32_sdwa v180, v173 dst_sel:BYTE_1 dst_unused:UNUSED_PRESERVE src0_sel:DWORD
	v_cvt_u32_f32_sdwa v181, v177 dst_sel:BYTE_1 dst_unused:UNUSED_PRESERVE src0_sel:DWORD
	v_cvt_u32_f32_sdwa v180, v174 dst_sel:BYTE_2 dst_unused:UNUSED_PRESERVE src0_sel:DWORD
	v_cvt_u32_f32_sdwa v181, v178 dst_sel:BYTE_2 dst_unused:UNUSED_PRESERVE src0_sel:DWORD
	v_cvt_u32_f32_sdwa v180, v175 dst_sel:BYTE_3 dst_unused:UNUSED_PRESERVE src0_sel:DWORD
	v_cvt_u32_f32_sdwa v181, v179 dst_sel:BYTE_3 dst_unused:UNUSED_PRESERVE src0_sel:DWORD
	ds_bpermute_b32 v180, v214, v180
	ds_bpermute_b32 v181, v214, v181
	v_pk_mul_f32 v[182:183], v[118:119], s[20:21] op_sel:[0,1] op_sel_hi:[1,1]
	v_pk_mul_f32 v[184:185], v[120:121], s[20:21] op_sel:[0,1] op_sel_hi:[1,1]
	v_pk_mul_f32 v[186:187], v[110:111], s[20:21] op_sel:[0,1] op_sel_hi:[1,1]
	v_pk_mul_f32 v[188:189], v[112:113], s[20:21] op_sel:[0,1] op_sel_hi:[1,1]
	v_exp_f32_e32 v182, v182
	v_exp_f32_e32 v183, v183
	v_exp_f32_e32 v184, v184
	v_exp_f32_e32 v185, v185
	v_exp_f32_e32 v186, v186
	v_exp_f32_e32 v187, v187
	v_exp_f32_e32 v188, v188
	v_exp_f32_e32 v189, v189
	v_pk_add_f32 v[182:183], v[182:183], 1.0 op_sel_hi:[1,0]
	v_pk_add_f32 v[184:185], v[184:185], 1.0 op_sel_hi:[1,0]
	v_pk_add_f32 v[186:187], v[186:187], 1.0 op_sel_hi:[1,0]
	v_pk_add_f32 v[188:189], v[188:189], 1.0 op_sel_hi:[1,0]
	v_rcp_f32_e32 v182, v182
	v_rcp_f32_e32 v183, v183
	v_rcp_f32_e32 v184, v184
	v_rcp_f32_e32 v185, v185
	v_rcp_f32_e32 v186, v186
	v_rcp_f32_e32 v187, v187
	v_rcp_f32_e32 v188, v188
	v_rcp_f32_e32 v189, v189
	s_nop 0
	v_pk_fma_f32 v[182:183], v[182:183], s[20:21], 0.5 op_sel_hi:[1,0,0]
	v_pk_fma_f32 v[184:185], v[184:185], s[20:21], 0.5 op_sel_hi:[1,0,0]
	v_pk_fma_f32 v[186:187], v[186:187], s[20:21], 0.5 op_sel_hi:[1,0,0]
	v_pk_fma_f32 v[188:189], v[188:189], s[20:21], 0.5 op_sel_hi:[1,0,0]
	v_max_f32_e32 v182, 1.0, v182
	v_max_f32_e32 v183, 1.0, v183
	v_max_f32_e32 v184, 1.0, v184
	v_max_f32_e32 v185, 1.0, v185
	v_max_f32_e32 v186, 1.0, v186
	v_max_f32_e32 v187, 1.0, v187
	v_max_f32_e32 v188, 1.0, v188
	v_max_f32_e32 v189, 1.0, v189
	v_cvt_u32_f32_e32 v190, v182
	v_cvt_u32_f32_e32 v191, v186
	v_cvt_u32_f32_sdwa v190, v183 dst_sel:BYTE_1 dst_unused:UNUSED_PRESERVE src0_sel:DWORD
	v_cvt_u32_f32_sdwa v191, v187 dst_sel:BYTE_1 dst_unused:UNUSED_PRESERVE src0_sel:DWORD
	v_cvt_u32_f32_sdwa v190, v184 dst_sel:BYTE_2 dst_unused:UNUSED_PRESERVE src0_sel:DWORD
	v_cvt_u32_f32_sdwa v191, v188 dst_sel:BYTE_2 dst_unused:UNUSED_PRESERVE src0_sel:DWORD
	v_cvt_u32_f32_sdwa v190, v185 dst_sel:BYTE_3 dst_unused:UNUSED_PRESERVE src0_sel:DWORD
	v_cvt_u32_f32_sdwa v191, v189 dst_sel:BYTE_3 dst_unused:UNUSED_PRESERVE src0_sel:DWORD
	ds_bpermute_b32 v190, v214, v190
	ds_bpermute_b32 v191, v214, v191
	s_waitcnt lgkmcnt(2)
; __device__ __forceinline__ float sigmoidf_(float x) { return __builtin_amdgcn_rcpf(1.f + __expf(-x)); }
;     __device__ __forceinline__ void operator()(f32x4 (&acc)[2][2][4][2], const pg8::Unit& u, int wr, int wc, int fr, int fq) const {
;     ...
;             for (int ai = 0; ai < 2; ++ai)
; #pragma unroll
;                 for (int m = 0; m < 4; ++m) {
;                     unsigned char* gp = gq + (size_t)(row0 + ai * 128 + m * 16) * 4096 + (u.pn - 28) * 256 + cin;
; #pragma unroll
;                     for (int bj = 0; bj < 2; ++bj) { unsigned w2[2];
; #pragma unroll
;                         for (int n = 0; n < 2; ++n) {
;                             const f32x4 v = acc[ai][bj][m][n];
;                             const unsigned b0 = (unsigned)(sigmoidf_(v[0]) * 255.f + 0.5f), b1 = (unsigned)(sigmoidf_(v[1]) * 255.f + 0.5f),
;                                            b2 = (unsigned)(sigmoidf_(v[2]) * 255.f + 0.5f), b3 = (unsigned)(sigmoidf_(v[3]) * 255.f + 0.5f);
;                             w2[n] = b0 | (b1 << 8) | (b2 << 16) | (b3 << 24);
;                         }
;                         u32x2 o = {w2[0], w2[1]}; *(u32x2*)(gp + bj * 128) = o; }
	global_store_dwordx2 v[192:193], v[180:181], off
	v_pk_mul_f32 v[172:173], v[114:115], s[20:21] op_sel:[0,1] op_sel_hi:[1,1]
	v_pk_mul_f32 v[174:175], v[116:117], s[20:21] op_sel:[0,1] op_sel_hi:[1,1]
	v_pk_mul_f32 v[176:177], v[106:107], s[20:21] op_sel:[0,1] op_sel_hi:[1,1]
	v_pk_mul_f32 v[178:179], v[108:109], s[20:21] op_sel:[0,1] op_sel_hi:[1,1]
	v_exp_f32_e32 v172, v172
	v_exp_f32_e32 v173, v173
	v_exp_f32_e32 v174, v174
	v_exp_f32_e32 v175, v175
	v_exp_f32_e32 v176, v176
	v_exp_f32_e32 v177, v177
	v_exp_f32_e32 v178, v178
	v_exp_f32_e32 v179, v179
	v_pk_add_f32 v[172:173], v[172:173], 1.0 op_sel_hi:[1,0]
	v_pk_add_f32 v[174:175], v[174:175], 1.0 op_sel_hi:[1,0]
	v_pk_add_f32 v[176:177], v[176:177], 1.0 op_sel_hi:[1,0]
	v_pk_add_f32 v[178:179], v[178:179], 1.0 op_sel_hi:[1,0]
	v_rcp_f32_e32 v172, v172
	v_rcp_f32_e32 v173, v173
	v_rcp_f32_e32 v174, v174
	v_rcp_f32_e32 v175, v175
	v_rcp_f32_e32 v176, v176
	v_rcp_f32_e32 v177, v177
	v_rcp_f32_e32 v178, v178
	v_rcp_f32_e32 v179, v179
	s_mov_b64 s[0:1], 0x10000
	v_lshl_add_u64 v[196:197], v[192:193], 0, s[0:1]
	v_pk_fma_f32 v[172:173], v[172:173], s[20:21], 0.5 op_sel_hi:[1,0,0]
	v_pk_fma_f32 v[174:175], v[174:175], s[20:21], 0.5 op_sel_hi:[1,0,0]
	v_pk_fma_f32 v[176:177], v[176:177], s[20:21], 0.5 op_sel_hi:[1,0,0]
	v_pk_fma_f32 v[178:179], v[178:179], s[20:21], 0.5 op_sel_hi:[1,0,0]
	v_max_f32_e32 v172, 1.0, v172
	v_max_f32_e32 v173, 1.0, v173
	v_max_f32_e32 v174, 1.0, v174
	v_max_f32_e32 v175, 1.0, v175
	v_max_f32_e32 v176, 1.0, v176
	v_max_f32_e32 v177, 1.0, v177
	v_max_f32_e32 v178, 1.0, v178
	v_max_f32_e32 v179, 1.0, v179
	v_cvt_u32_f32_e32 v180, v172
	v_cvt_u32_f32_e32 v181, v176
	v_cvt_u32_f32_sdwa v180, v173 dst_sel:BYTE_1 dst_unused:UNUSED_PRESERVE src0_sel:DWORD
	v_cvt_u32_f32_sdwa v181, v177 dst_sel:BYTE_1 dst_unused:UNUSED_PRESERVE src0_sel:DWORD
	v_cvt_u32_f32_sdwa v180, v174 dst_sel:BYTE_2 dst_unused:UNUSED_PRESERVE src0_sel:DWORD
	v_cvt_u32_f32_sdwa v181, v178 dst_sel:BYTE_2 dst_unused:UNUSED_PRESERVE src0_sel:DWORD
	v_cvt_u32_f32_sdwa v180, v175 dst_sel:BYTE_3 dst_unused:UNUSED_PRESERVE src0_sel:DWORD
	v_cvt_u32_f32_sdwa v181, v179 dst_sel:BYTE_3 dst_unused:UNUSED_PRESERVE src0_sel:DWORD
	ds_bpermute_b32 v180, v214, v180
	ds_bpermute_b32 v181, v214, v181
	s_waitcnt lgkmcnt(2)
	global_store_dwordx2 v[192:193], v[190:191], off offset:128
	v_pk_mul_f32 v[182:183], v[98:99], s[20:21] op_sel:[0,1] op_sel_hi:[1,1]
	v_pk_mul_f32 v[184:185], v[100:101], s[20:21] op_sel:[0,1] op_sel_hi:[1,1]
	v_pk_mul_f32 v[186:187], v[90:91], s[20:21] op_sel:[0,1] op_sel_hi:[1,1]
	v_pk_mul_f32 v[188:189], v[92:93], s[20:21] op_sel:[0,1] op_sel_hi:[1,1]
	v_exp_f32_e32 v182, v182
	v_exp_f32_e32 v183, v183
	v_exp_f32_e32 v184, v184
	v_exp_f32_e32 v185, v185
	v_exp_f32_e32 v186, v186
	v_exp_f32_e32 v187, v187
	v_exp_f32_e32 v188, v188
	v_exp_f32_e32 v189, v189
	v_pk_add_f32 v[182:183], v[182:183], 1.0 op_sel_hi:[1,0]
	v_pk_add_f32 v[184:185], v[184:185], 1.0 op_sel_hi:[1,0]
	v_pk_add_f32 v[186:187], v[186:187], 1.0 op_sel_hi:[1,0]
	v_pk_add_f32 v[188:189], v[188:189], 1.0 op_sel_hi:[1,0]
	v_rcp_f32_e32 v182, v182
	v_rcp_f32_e32 v183, v183
	v_rcp_f32_e32 v184, v184
	v_rcp_f32_e32 v185, v185
	v_rcp_f32_e32 v186, v186
	v_rcp_f32_e32 v187, v187
	v_rcp_f32_e32 v188, v188
	v_rcp_f32_e32 v189, v189
	s_nop 0
	v_pk_fma_f32 v[182:183], v[182:183], s[20:21], 0.5 op_sel_hi:[1,0,0]
	v_pk_fma_f32 v[184:185], v[184:185], s[20:21], 0.5 op_sel_hi:[1,0,0]
	v_pk_fma_f32 v[186:187], v[186:187], s[20:21], 0.5 op_sel_hi:[1,0,0]
	v_pk_fma_f32 v[188:189], v[188:189], s[20:21], 0.5 op_sel_hi:[1,0,0]
	v_max_f32_e32 v182, 1.0, v182
	v_max_f32_e32 v183, 1.0, v183
	v_max_f32_e32 v184, 1.0, v184
	v_max_f32_e32 v185, 1.0, v185
	v_max_f32_e32 v186, 1.0, v186
	v_max_f32_e32 v187, 1.0, v187
	v_max_f32_e32 v188, 1.0, v188
	v_max_f32_e32 v189, 1.0, v189
	v_cvt_u32_f32_e32 v190, v182
	v_cvt_u32_f32_e32 v191, v186
	v_cvt_u32_f32_sdwa v190, v183 dst_sel:BYTE_1 dst_unused:UNUSED_PRESERVE src0_sel:DWORD
	v_cvt_u32_f32_sdwa v191, v187 dst_sel:BYTE_1 dst_unused:UNUSED_PRESERVE src0_sel:DWORD
	v_cvt_u32_f32_sdwa v190, v184 dst_sel:BYTE_2 dst_unused:UNUSED_PRESERVE src0_sel:DWORD
	v_cvt_u32_f32_sdwa v191, v188 dst_sel:BYTE_2 dst_unused:UNUSED_PRESERVE src0_sel:DWORD
	v_cvt_u32_f32_sdwa v190, v185 dst_sel:BYTE_3 dst_unused:UNUSED_PRESERVE src0_sel:DWORD
	v_cvt_u32_f32_sdwa v191, v189 dst_sel:BYTE_3 dst_unused:UNUSED_PRESERVE src0_sel:DWORD
	ds_bpermute_b32 v190, v214, v190
	ds_bpermute_b32 v191, v214, v191
	s_waitcnt lgkmcnt(2)
; __device__ __forceinline__ float sigmoidf_(float x) { return __builtin_amdgcn_rcpf(1.f + __expf(-x)); }
;     __device__ __forceinline__ void operator()(f32x4 (&acc)[2][2][4][2], const pg8::Unit& u, int wr, int wc, int fr, int fq) const {
;     ...
;             for (int ai = 0; ai < 2; ++ai)
; #pragma unroll
;                 for (int m = 0; m < 4; ++m) {
;                     unsigned char* gp = gq + (size_t)(row0 + ai * 128 + m * 16) * 4096 + (u.pn - 28) * 256 + cin;
; #pragma unroll
;                     for (int bj = 0; bj < 2; ++bj) { unsigned w2[2];
; #pragma unroll
;                         for (int n = 0; n < 2; ++n) {
;                             const f32x4 v = acc[ai][bj][m][n];
;                             const unsigned b0 = (unsigned)(sigmoidf_(v[0]) * 255.f + 0.5f), b1 = (unsigned)(sigmoidf_(v[1]) * 255.f + 0.5f),
;                                            b2 = (unsigned)(sigmoidf_(v[2]) * 255.f + 0.5f), b3 = (unsigned)(sigmoidf_(v[3]) * 255.f + 0.5f);
;                             w2[n] = b0 | (b1 << 8) | (b2 << 16) | (b3 << 24);
;                         }
;                         u32x2 o = {w2[0], w2[1]}; *(u32x2*)(gp + bj * 128) = o; }
	global_store_dwordx2 v[196:197], v[180:181], off
	v_pk_mul_f32 v[172:173], v[102:103], s[20:21] op_sel:[0,1] op_sel_hi:[1,1]
	v_pk_mul_f32 v[174:175], v[104:105], s[20:21] op_sel:[0,1] op_sel_hi:[1,1]
	v_pk_mul_f32 v[176:177], v[94:95], s[20:21] op_sel:[0,1] op_sel_hi:[1,1]
	v_pk_mul_f32 v[178:179], v[96:97], s[20:21] op_sel:[0,1] op_sel_hi:[1,1]
	v_exp_f32_e32 v172, v172
	v_exp_f32_e32 v173, v173
	v_exp_f32_e32 v174, v174
	v_exp_f32_e32 v175, v175
	v_exp_f32_e32 v176, v176
	v_exp_f32_e32 v177, v177
	v_exp_f32_e32 v178, v178
	v_exp_f32_e32 v179, v179
	v_pk_add_f32 v[172:173], v[172:173], 1.0 op_sel_hi:[1,0]
	v_pk_add_f32 v[174:175], v[174:175], 1.0 op_sel_hi:[1,0]
	v_pk_add_f32 v[176:177], v[176:177], 1.0 op_sel_hi:[1,0]
	v_pk_add_f32 v[178:179], v[178:179], 1.0 op_sel_hi:[1,0]
	v_rcp_f32_e32 v172, v172
	v_rcp_f32_e32 v173, v173
	v_rcp_f32_e32 v174, v174
	v_rcp_f32_e32 v175, v175
	v_rcp_f32_e32 v176, v176
	v_rcp_f32_e32 v177, v177
	v_rcp_f32_e32 v178, v178
	v_rcp_f32_e32 v179, v179
	s_mov_b64 s[0:1], 0x20000
	v_lshl_add_u64 v[194:195], v[192:193], 0, s[0:1]
	v_pk_fma_f32 v[172:173], v[172:173], s[20:21], 0.5 op_sel_hi:[1,0,0]
	v_pk_fma_f32 v[174:175], v[174:175], s[20:21], 0.5 op_sel_hi:[1,0,0]
	v_pk_fma_f32 v[176:177], v[176:177], s[20:21], 0.5 op_sel_hi:[1,0,0]
	v_pk_fma_f32 v[178:179], v[178:179], s[20:21], 0.5 op_sel_hi:[1,0,0]
	v_max_f32_e32 v172, 1.0, v172
	v_max_f32_e32 v173, 1.0, v173
	v_max_f32_e32 v174, 1.0, v174
	v_max_f32_e32 v175, 1.0, v175
	v_max_f32_e32 v176, 1.0, v176
	v_max_f32_e32 v177, 1.0, v177
	v_max_f32_e32 v178, 1.0, v178
	v_max_f32_e32 v179, 1.0, v179
	v_cvt_u32_f32_e32 v180, v172
	v_cvt_u32_f32_e32 v181, v176
	v_cvt_u32_f32_sdwa v180, v173 dst_sel:BYTE_1 dst_unused:UNUSED_PRESERVE src0_sel:DWORD
	v_cvt_u32_f32_sdwa v181, v177 dst_sel:BYTE_1 dst_unused:UNUSED_PRESERVE src0_sel:DWORD
	v_cvt_u32_f32_sdwa v180, v174 dst_sel:BYTE_2 dst_unused:UNUSED_PRESERVE src0_sel:DWORD
	v_cvt_u32_f32_sdwa v181, v178 dst_sel:BYTE_2 dst_unused:UNUSED_PRESERVE src0_sel:DWORD
	v_cvt_u32_f32_sdwa v180, v175 dst_sel:BYTE_3 dst_unused:UNUSED_PRESERVE src0_sel:DWORD
	v_cvt_u32_f32_sdwa v181, v179 dst_sel:BYTE_3 dst_unused:UNUSED_PRESERVE src0_sel:DWORD
	ds_bpermute_b32 v180, v214, v180
	ds_bpermute_b32 v181, v214, v181
	s_waitcnt lgkmcnt(2)
	global_store_dwordx2 v[196:197], v[190:191], off offset:128
	v_pk_mul_f32 v[182:183], v[82:83], s[20:21] op_sel:[0,1] op_sel_hi:[1,1]
	v_pk_mul_f32 v[184:185], v[84:85], s[20:21] op_sel:[0,1] op_sel_hi:[1,1]
	v_pk_mul_f32 v[186:187], v[74:75], s[20:21] op_sel:[0,1] op_sel_hi:[1,1]
	v_pk_mul_f32 v[188:189], v[76:77], s[20:21] op_sel:[0,1] op_sel_hi:[1,1]
	v_exp_f32_e32 v182, v182
	v_exp_f32_e32 v183, v183
	v_exp_f32_e32 v184, v184
	v_exp_f32_e32 v185, v185
	v_exp_f32_e32 v186, v186
	v_exp_f32_e32 v187, v187
	v_exp_f32_e32 v188, v188
	v_exp_f32_e32 v189, v189
	v_pk_add_f32 v[182:183], v[182:183], 1.0 op_sel_hi:[1,0]
	v_pk_add_f32 v[184:185], v[184:185], 1.0 op_sel_hi:[1,0]
	v_pk_add_f32 v[186:187], v[186:187], 1.0 op_sel_hi:[1,0]
	v_pk_add_f32 v[188:189], v[188:189], 1.0 op_sel_hi:[1,0]
	v_rcp_f32_e32 v182, v182
	v_rcp_f32_e32 v183, v183
	v_rcp_f32_e32 v184, v184
	v_rcp_f32_e32 v185, v185
	v_rcp_f32_e32 v186, v186
	v_rcp_f32_e32 v187, v187
	v_rcp_f32_e32 v188, v188
	v_rcp_f32_e32 v189, v189
	s_nop 0
	v_pk_fma_f32 v[182:183], v[182:183], s[20:21], 0.5 op_sel_hi:[1,0,0]
	v_pk_fma_f32 v[184:185], v[184:185], s[20:21], 0.5 op_sel_hi:[1,0,0]
	v_pk_fma_f32 v[186:187], v[186:187], s[20:21], 0.5 op_sel_hi:[1,0,0]
	v_pk_fma_f32 v[188:189], v[188:189], s[20:21], 0.5 op_sel_hi:[1,0,0]
	v_max_f32_e32 v182, 1.0, v182
	v_max_f32_e32 v183, 1.0, v183
	v_max_f32_e32 v184, 1.0, v184
	v_max_f32_e32 v185, 1.0, v185
	v_max_f32_e32 v186, 1.0, v186
	v_max_f32_e32 v187, 1.0, v187
	v_max_f32_e32 v188, 1.0, v188
	v_max_f32_e32 v189, 1.0, v189
	v_cvt_u32_f32_e32 v190, v182
	v_cvt_u32_f32_e32 v191, v186
	v_cvt_u32_f32_sdwa v190, v183 dst_sel:BYTE_1 dst_unused:UNUSED_PRESERVE src0_sel:DWORD
	v_cvt_u32_f32_sdwa v191, v187 dst_sel:BYTE_1 dst_unused:UNUSED_PRESERVE src0_sel:DWORD
	v_cvt_u32_f32_sdwa v190, v184 dst_sel:BYTE_2 dst_unused:UNUSED_PRESERVE src0_sel:DWORD
	v_cvt_u32_f32_sdwa v191, v188 dst_sel:BYTE_2 dst_unused:UNUSED_PRESERVE src0_sel:DWORD
	v_cvt_u32_f32_sdwa v190, v185 dst_sel:BYTE_3 dst_unused:UNUSED_PRESERVE src0_sel:DWORD
	v_cvt_u32_f32_sdwa v191, v189 dst_sel:BYTE_3 dst_unused:UNUSED_PRESERVE src0_sel:DWORD
	ds_bpermute_b32 v190, v214, v190
	ds_bpermute_b32 v191, v214, v191
	s_waitcnt lgkmcnt(2)
	global_store_dwordx2 v[194:195], v[180:181], off
	v_pk_mul_f32 v[172:173], v[86:87], s[20:21] op_sel:[0,1] op_sel_hi:[1,1]
	v_pk_mul_f32 v[174:175], v[88:89], s[20:21] op_sel:[0,1] op_sel_hi:[1,1]
	v_pk_mul_f32 v[176:177], v[78:79], s[20:21] op_sel:[0,1] op_sel_hi:[1,1]
	v_pk_mul_f32 v[178:179], v[80:81], s[20:21] op_sel:[0,1] op_sel_hi:[1,1]
	v_exp_f32_e32 v172, v172
	v_exp_f32_e32 v173, v173
	v_exp_f32_e32 v174, v174
	v_exp_f32_e32 v175, v175
	v_exp_f32_e32 v176, v176
	v_exp_f32_e32 v177, v177
	v_exp_f32_e32 v178, v178
	v_exp_f32_e32 v179, v179
	v_pk_add_f32 v[172:173], v[172:173], 1.0 op_sel_hi:[1,0]
	v_pk_add_f32 v[174:175], v[174:175], 1.0 op_sel_hi:[1,0]
	v_pk_add_f32 v[176:177], v[176:177], 1.0 op_sel_hi:[1,0]
	v_pk_add_f32 v[178:179], v[178:179], 1.0 op_sel_hi:[1,0]
	v_rcp_f32_e32 v172, v172
	v_rcp_f32_e32 v173, v173
	v_rcp_f32_e32 v174, v174
	v_rcp_f32_e32 v175, v175
	v_rcp_f32_e32 v176, v176
	v_rcp_f32_e32 v177, v177
	v_rcp_f32_e32 v178, v178
	v_rcp_f32_e32 v179, v179
	s_mov_b64 s[0:1], 0x30000
	v_lshl_add_u64 v[196:197], v[192:193], 0, s[0:1]
	v_pk_fma_f32 v[172:173], v[172:173], s[20:21], 0.5 op_sel_hi:[1,0,0]
	v_pk_fma_f32 v[174:175], v[174:175], s[20:21], 0.5 op_sel_hi:[1,0,0]
	v_pk_fma_f32 v[176:177], v[176:177], s[20:21], 0.5 op_sel_hi:[1,0,0]
	v_pk_fma_f32 v[178:179], v[178:179], s[20:21], 0.5 op_sel_hi:[1,0,0]
	v_max_f32_e32 v172, 1.0, v172
	v_max_f32_e32 v173, 1.0, v173
	v_max_f32_e32 v174, 1.0, v174
	v_max_f32_e32 v175, 1.0, v175
	v_max_f32_e32 v176, 1.0, v176
	v_max_f32_e32 v177, 1.0, v177
	v_max_f32_e32 v178, 1.0, v178
	v_max_f32_e32 v179, 1.0, v179
	v_cvt_u32_f32_e32 v180, v172
	v_cvt_u32_f32_e32 v181, v176
	v_cvt_u32_f32_sdwa v180, v173 dst_sel:BYTE_1 dst_unused:UNUSED_PRESERVE src0_sel:DWORD
	v_cvt_u32_f32_sdwa v181, v177 dst_sel:BYTE_1 dst_unused:UNUSED_PRESERVE src0_sel:DWORD
	v_cvt_u32_f32_sdwa v180, v174 dst_sel:BYTE_2 dst_unused:UNUSED_PRESERVE src0_sel:DWORD
	v_cvt_u32_f32_sdwa v181, v178 dst_sel:BYTE_2 dst_unused:UNUSED_PRESERVE src0_sel:DWORD
	v_cvt_u32_f32_sdwa v180, v175 dst_sel:BYTE_3 dst_unused:UNUSED_PRESERVE src0_sel:DWORD
	v_cvt_u32_f32_sdwa v181, v179 dst_sel:BYTE_3 dst_unused:UNUSED_PRESERVE src0_sel:DWORD
	ds_bpermute_b32 v180, v214, v180
	ds_bpermute_b32 v181, v214, v181
	s_waitcnt lgkmcnt(2)
; __device__ __forceinline__ float sigmoidf_(float x) { return __builtin_amdgcn_rcpf(1.f + __expf(-x)); }
;     __device__ __forceinline__ void operator()(f32x4 (&acc)[2][2][4][2], const pg8::Unit& u, int wr, int wc, int fr, int fq) const {
;     ...
;             for (int ai = 0; ai < 2; ++ai)
; #pragma unroll
;                 for (int m = 0; m < 4; ++m) {
;                     unsigned char* gp = gq + (size_t)(row0 + ai * 128 + m * 16) * 4096 + (u.pn - 28) * 256 + cin;
; #pragma unroll
;                     for (int bj = 0; bj < 2; ++bj) { unsigned w2[2];
; #pragma unroll
;                         for (int n = 0; n < 2; ++n) {
;                             const f32x4 v = acc[ai][bj][m][n];
;                             const unsigned b0 = (unsigned)(sigmoidf_(v[0]) * 255.f + 0.5f), b1 = (unsigned)(sigmoidf_(v[1]) * 255.f + 0.5f),
;                                            b2 = (unsigned)(sigmoidf_(v[2]) * 255.f + 0.5f), b3 = (unsigned)(sigmoidf_(v[3]) * 255.f + 0.5f);
;                             w2[n] = b0 | (b1 << 8) | (b2 << 16) | (b3 << 24);
;                         }
;                         u32x2 o = {w2[0], w2[1]}; *(u32x2*)(gp + bj * 128) = o; }
	global_store_dwordx2 v[194:195], v[190:191], off offset:128
	v_pk_mul_f32 v[182:183], v[70:71], s[20:21] op_sel:[0,1] op_sel_hi:[1,1]
	v_pk_mul_f32 v[184:185], v[72:73], s[20:21] op_sel:[0,1] op_sel_hi:[1,1]
	v_pk_mul_f32 v[186:187], v[66:67], s[20:21] op_sel:[0,1] op_sel_hi:[1,1]
	v_pk_mul_f32 v[188:189], v[68:69], s[20:21] op_sel:[0,1] op_sel_hi:[1,1]
	v_exp_f32_e32 v182, v182
	v_exp_f32_e32 v183, v183
	v_exp_f32_e32 v184, v184
	v_exp_f32_e32 v185, v185
	v_exp_f32_e32 v186, v186
	v_exp_f32_e32 v187, v187
	v_exp_f32_e32 v188, v188
	v_exp_f32_e32 v189, v189
	v_pk_add_f32 v[182:183], v[182:183], 1.0 op_sel_hi:[1,0]
	v_pk_add_f32 v[184:185], v[184:185], 1.0 op_sel_hi:[1,0]
	v_pk_add_f32 v[186:187], v[186:187], 1.0 op_sel_hi:[1,0]
	v_pk_add_f32 v[188:189], v[188:189], 1.0 op_sel_hi:[1,0]
	v_rcp_f32_e32 v182, v182
	v_rcp_f32_e32 v183, v183
	v_rcp_f32_e32 v184, v184
	v_rcp_f32_e32 v185, v185
	v_rcp_f32_e32 v186, v186
	v_rcp_f32_e32 v187, v187
	v_rcp_f32_e32 v188, v188
	v_rcp_f32_e32 v189, v189
	s_nop 0
	v_pk_fma_f32 v[182:183], v[182:183], s[20:21], 0.5 op_sel_hi:[1,0,0]
	v_pk_fma_f32 v[184:185], v[184:185], s[20:21], 0.5 op_sel_hi:[1,0,0]
	v_pk_fma_f32 v[186:187], v[186:187], s[20:21], 0.5 op_sel_hi:[1,0,0]
	v_pk_fma_f32 v[188:189], v[188:189], s[20:21], 0.5 op_sel_hi:[1,0,0]
	v_max_f32_e32 v182, 1.0, v182
	v_max_f32_e32 v183, 1.0, v183
	v_max_f32_e32 v184, 1.0, v184
	v_max_f32_e32 v185, 1.0, v185
	v_max_f32_e32 v186, 1.0, v186
	v_max_f32_e32 v187, 1.0, v187
	v_max_f32_e32 v188, 1.0, v188
	v_max_f32_e32 v189, 1.0, v189
	v_cvt_u32_f32_e32 v190, v182
	v_cvt_u32_f32_e32 v191, v186
	v_cvt_u32_f32_sdwa v190, v183 dst_sel:BYTE_1 dst_unused:UNUSED_PRESERVE src0_sel:DWORD
	v_cvt_u32_f32_sdwa v191, v187 dst_sel:BYTE_1 dst_unused:UNUSED_PRESERVE src0_sel:DWORD
	v_cvt_u32_f32_sdwa v190, v184 dst_sel:BYTE_2 dst_unused:UNUSED_PRESERVE src0_sel:DWORD
	v_cvt_u32_f32_sdwa v191, v188 dst_sel:BYTE_2 dst_unused:UNUSED_PRESERVE src0_sel:DWORD
	v_cvt_u32_f32_sdwa v190, v185 dst_sel:BYTE_3 dst_unused:UNUSED_PRESERVE src0_sel:DWORD
	v_cvt_u32_f32_sdwa v191, v189 dst_sel:BYTE_3 dst_unused:UNUSED_PRESERVE src0_sel:DWORD
	ds_bpermute_b32 v190, v214, v190
	ds_bpermute_b32 v191, v214, v191
	s_waitcnt lgkmcnt(2)
	global_store_dwordx2 v[196:197], v[180:181], off
	v_pk_mul_f32 v[172:173], v[62:63], s[20:21] op_sel:[0,1] op_sel_hi:[1,1]
	v_pk_mul_f32 v[174:175], v[64:65], s[20:21] op_sel:[0,1] op_sel_hi:[1,1]
	v_pk_mul_f32 v[176:177], v[58:59], s[20:21] op_sel:[0,1] op_sel_hi:[1,1]
	v_pk_mul_f32 v[178:179], v[60:61], s[20:21] op_sel:[0,1] op_sel_hi:[1,1]
	v_exp_f32_e32 v172, v172
	v_exp_f32_e32 v173, v173
	v_exp_f32_e32 v174, v174
	v_exp_f32_e32 v175, v175
	v_exp_f32_e32 v176, v176
	v_exp_f32_e32 v177, v177
	v_exp_f32_e32 v178, v178
	v_exp_f32_e32 v179, v179
	v_pk_add_f32 v[172:173], v[172:173], 1.0 op_sel_hi:[1,0]
	v_pk_add_f32 v[174:175], v[174:175], 1.0 op_sel_hi:[1,0]
	v_pk_add_f32 v[176:177], v[176:177], 1.0 op_sel_hi:[1,0]
	v_pk_add_f32 v[178:179], v[178:179], 1.0 op_sel_hi:[1,0]
	v_rcp_f32_e32 v172, v172
	v_rcp_f32_e32 v173, v173
	v_rcp_f32_e32 v174, v174
	v_rcp_f32_e32 v175, v175
	v_rcp_f32_e32 v176, v176
	v_rcp_f32_e32 v177, v177
	v_rcp_f32_e32 v178, v178
	v_rcp_f32_e32 v179, v179
	s_mov_b64 s[0:1], 0x80000
	v_lshl_add_u64 v[194:195], v[192:193], 0, s[0:1]
	v_pk_fma_f32 v[172:173], v[172:173], s[20:21], 0.5 op_sel_hi:[1,0,0]
	v_pk_fma_f32 v[174:175], v[174:175], s[20:21], 0.5 op_sel_hi:[1,0,0]
	v_pk_fma_f32 v[176:177], v[176:177], s[20:21], 0.5 op_sel_hi:[1,0,0]
	v_pk_fma_f32 v[178:179], v[178:179], s[20:21], 0.5 op_sel_hi:[1,0,0]
	v_max_f32_e32 v172, 1.0, v172
	v_max_f32_e32 v173, 1.0, v173
	v_max_f32_e32 v174, 1.0, v174
	v_max_f32_e32 v175, 1.0, v175
	v_max_f32_e32 v176, 1.0, v176
	v_max_f32_e32 v177, 1.0, v177
	v_max_f32_e32 v178, 1.0, v178
	v_max_f32_e32 v179, 1.0, v179
	v_cvt_u32_f32_e32 v180, v172
	v_cvt_u32_f32_e32 v181, v176
	v_cvt_u32_f32_sdwa v180, v173 dst_sel:BYTE_1 dst_unused:UNUSED_PRESERVE src0_sel:DWORD
	v_cvt_u32_f32_sdwa v181, v177 dst_sel:BYTE_1 dst_unused:UNUSED_PRESERVE src0_sel:DWORD
	v_cvt_u32_f32_sdwa v180, v174 dst_sel:BYTE_2 dst_unused:UNUSED_PRESERVE src0_sel:DWORD
	v_cvt_u32_f32_sdwa v181, v178 dst_sel:BYTE_2 dst_unused:UNUSED_PRESERVE src0_sel:DWORD
	v_cvt_u32_f32_sdwa v180, v175 dst_sel:BYTE_3 dst_unused:UNUSED_PRESERVE src0_sel:DWORD
	v_cvt_u32_f32_sdwa v181, v179 dst_sel:BYTE_3 dst_unused:UNUSED_PRESERVE src0_sel:DWORD
	ds_bpermute_b32 v180, v214, v180
	ds_bpermute_b32 v181, v214, v181
	s_waitcnt lgkmcnt(2)
	global_store_dwordx2 v[196:197], v[190:191], off offset:128
	v_pk_mul_f32 v[182:183], v[54:55], s[20:21] op_sel:[0,1] op_sel_hi:[1,1]
	v_pk_mul_f32 v[184:185], v[56:57], s[20:21] op_sel:[0,1] op_sel_hi:[1,1]
	v_pk_mul_f32 v[186:187], v[46:47], s[20:21] op_sel:[0,1] op_sel_hi:[1,1]
	v_pk_mul_f32 v[188:189], v[48:49], s[20:21] op_sel:[0,1] op_sel_hi:[1,1]
	v_exp_f32_e32 v182, v182
	v_exp_f32_e32 v183, v183
	v_exp_f32_e32 v184, v184
	v_exp_f32_e32 v185, v185
	v_exp_f32_e32 v186, v186
	v_exp_f32_e32 v187, v187
	v_exp_f32_e32 v188, v188
	v_exp_f32_e32 v189, v189
	v_pk_add_f32 v[182:183], v[182:183], 1.0 op_sel_hi:[1,0]
	v_pk_add_f32 v[184:185], v[184:185], 1.0 op_sel_hi:[1,0]
	v_pk_add_f32 v[186:187], v[186:187], 1.0 op_sel_hi:[1,0]
	v_pk_add_f32 v[188:189], v[188:189], 1.0 op_sel_hi:[1,0]
	v_rcp_f32_e32 v182, v182
	v_rcp_f32_e32 v183, v183
	v_rcp_f32_e32 v184, v184
	v_rcp_f32_e32 v185, v185
	v_rcp_f32_e32 v186, v186
	v_rcp_f32_e32 v187, v187
	v_rcp_f32_e32 v188, v188
	v_rcp_f32_e32 v189, v189
	s_nop 0
	v_pk_fma_f32 v[182:183], v[182:183], s[20:21], 0.5 op_sel_hi:[1,0,0]
	v_pk_fma_f32 v[184:185], v[184:185], s[20:21], 0.5 op_sel_hi:[1,0,0]
	v_pk_fma_f32 v[186:187], v[186:187], s[20:21], 0.5 op_sel_hi:[1,0,0]
	v_pk_fma_f32 v[188:189], v[188:189], s[20:21], 0.5 op_sel_hi:[1,0,0]
	v_max_f32_e32 v182, 1.0, v182
	v_max_f32_e32 v183, 1.0, v183
	v_max_f32_e32 v184, 1.0, v184
	v_max_f32_e32 v185, 1.0, v185
	v_max_f32_e32 v186, 1.0, v186
	v_max_f32_e32 v187, 1.0, v187
	v_max_f32_e32 v188, 1.0, v188
	v_max_f32_e32 v189, 1.0, v189
	v_cvt_u32_f32_e32 v190, v182
	v_cvt_u32_f32_e32 v191, v186
	v_cvt_u32_f32_sdwa v190, v183 dst_sel:BYTE_1 dst_unused:UNUSED_PRESERVE src0_sel:DWORD
	v_cvt_u32_f32_sdwa v191, v187 dst_sel:BYTE_1 dst_unused:UNUSED_PRESERVE src0_sel:DWORD
	v_cvt_u32_f32_sdwa v190, v184 dst_sel:BYTE_2 dst_unused:UNUSED_PRESERVE src0_sel:DWORD
	v_cvt_u32_f32_sdwa v191, v188 dst_sel:BYTE_2 dst_unused:UNUSED_PRESERVE src0_sel:DWORD
	v_cvt_u32_f32_sdwa v190, v185 dst_sel:BYTE_3 dst_unused:UNUSED_PRESERVE src0_sel:DWORD
	v_cvt_u32_f32_sdwa v191, v189 dst_sel:BYTE_3 dst_unused:UNUSED_PRESERVE src0_sel:DWORD
	ds_bpermute_b32 v190, v214, v190
	ds_bpermute_b32 v191, v214, v191
	s_waitcnt lgkmcnt(2)
; __device__ __forceinline__ float sigmoidf_(float x) { return __builtin_amdgcn_rcpf(1.f + __expf(-x)); }
;     __device__ __forceinline__ void operator()(f32x4 (&acc)[2][2][4][2], const pg8::Unit& u, int wr, int wc, int fr, int fq) const {
;     ...
;             for (int ai = 0; ai < 2; ++ai)
; #pragma unroll
;                 for (int m = 0; m < 4; ++m) {
;                     unsigned char* gp = gq + (size_t)(row0 + ai * 128 + m * 16) * 4096 + (u.pn - 28) * 256 + cin;
; #pragma unroll
;                     for (int bj = 0; bj < 2; ++bj) { unsigned w2[2];
; #pragma unroll
;                         for (int n = 0; n < 2; ++n) {
;                             const f32x4 v = acc[ai][bj][m][n];
;                             const unsigned b0 = (unsigned)(sigmoidf_(v[0]) * 255.f + 0.5f), b1 = (unsigned)(sigmoidf_(v[1]) * 255.f + 0.5f),
;                                            b2 = (unsigned)(sigmoidf_(v[2]) * 255.f + 0.5f), b3 = (unsigned)(sigmoidf_(v[3]) * 255.f + 0.5f);
;                             w2[n] = b0 | (b1 << 8) | (b2 << 16) | (b3 << 24);
;                         }
;                         u32x2 o = {w2[0], w2[1]}; *(u32x2*)(gp + bj * 128) = o; }
	global_store_dwordx2 v[194:195], v[180:181], off
	v_pk_mul_f32 v[172:173], v[50:51], s[20:21] op_sel:[0,1] op_sel_hi:[1,1]
	v_pk_mul_f32 v[174:175], v[52:53], s[20:21] op_sel:[0,1] op_sel_hi:[1,1]
	v_pk_mul_f32 v[176:177], v[42:43], s[20:21] op_sel:[0,1] op_sel_hi:[1,1]
	v_pk_mul_f32 v[178:179], v[44:45], s[20:21] op_sel:[0,1] op_sel_hi:[1,1]
	v_exp_f32_e32 v172, v172
	v_exp_f32_e32 v173, v173
	v_exp_f32_e32 v174, v174
	v_exp_f32_e32 v175, v175
	v_exp_f32_e32 v176, v176
	v_exp_f32_e32 v177, v177
	v_exp_f32_e32 v178, v178
	v_exp_f32_e32 v179, v179
	v_pk_add_f32 v[172:173], v[172:173], 1.0 op_sel_hi:[1,0]
	v_pk_add_f32 v[174:175], v[174:175], 1.0 op_sel_hi:[1,0]
	v_pk_add_f32 v[176:177], v[176:177], 1.0 op_sel_hi:[1,0]
	v_pk_add_f32 v[178:179], v[178:179], 1.0 op_sel_hi:[1,0]
	v_rcp_f32_e32 v172, v172
	v_rcp_f32_e32 v173, v173
	v_rcp_f32_e32 v174, v174
	v_rcp_f32_e32 v175, v175
	v_rcp_f32_e32 v176, v176
	v_rcp_f32_e32 v177, v177
	v_rcp_f32_e32 v178, v178
	v_rcp_f32_e32 v179, v179
	s_mov_b64 s[0:1], 0x90000
	v_lshl_add_u64 v[196:197], v[192:193], 0, s[0:1]
	v_pk_fma_f32 v[172:173], v[172:173], s[20:21], 0.5 op_sel_hi:[1,0,0]
	v_pk_fma_f32 v[174:175], v[174:175], s[20:21], 0.5 op_sel_hi:[1,0,0]
	v_pk_fma_f32 v[176:177], v[176:177], s[20:21], 0.5 op_sel_hi:[1,0,0]
	v_pk_fma_f32 v[178:179], v[178:179], s[20:21], 0.5 op_sel_hi:[1,0,0]
	v_max_f32_e32 v172, 1.0, v172
	v_max_f32_e32 v173, 1.0, v173
	v_max_f32_e32 v174, 1.0, v174
	v_max_f32_e32 v175, 1.0, v175
	v_max_f32_e32 v176, 1.0, v176
	v_max_f32_e32 v177, 1.0, v177
	v_max_f32_e32 v178, 1.0, v178
	v_max_f32_e32 v179, 1.0, v179
	v_cvt_u32_f32_e32 v180, v172
	v_cvt_u32_f32_e32 v181, v176
	v_cvt_u32_f32_sdwa v180, v173 dst_sel:BYTE_1 dst_unused:UNUSED_PRESERVE src0_sel:DWORD
	v_cvt_u32_f32_sdwa v181, v177 dst_sel:BYTE_1 dst_unused:UNUSED_PRESERVE src0_sel:DWORD
	v_cvt_u32_f32_sdwa v180, v174 dst_sel:BYTE_2 dst_unused:UNUSED_PRESERVE src0_sel:DWORD
	v_cvt_u32_f32_sdwa v181, v178 dst_sel:BYTE_2 dst_unused:UNUSED_PRESERVE src0_sel:DWORD
	v_cvt_u32_f32_sdwa v180, v175 dst_sel:BYTE_3 dst_unused:UNUSED_PRESERVE src0_sel:DWORD
	v_cvt_u32_f32_sdwa v181, v179 dst_sel:BYTE_3 dst_unused:UNUSED_PRESERVE src0_sel:DWORD
	ds_bpermute_b32 v180, v214, v180
	ds_bpermute_b32 v181, v214, v181
	s_waitcnt lgkmcnt(2)
	global_store_dwordx2 v[194:195], v[190:191], off offset:128
	v_pk_mul_f32 v[182:183], v[34:35], s[20:21] op_sel:[0,1] op_sel_hi:[1,1]
	v_pk_mul_f32 v[184:185], v[36:37], s[20:21] op_sel:[0,1] op_sel_hi:[1,1]
	v_pk_mul_f32 v[186:187], v[26:27], s[20:21] op_sel:[0,1] op_sel_hi:[1,1]
	v_pk_mul_f32 v[188:189], v[28:29], s[20:21] op_sel:[0,1] op_sel_hi:[1,1]
	v_exp_f32_e32 v182, v182
	v_exp_f32_e32 v183, v183
	v_exp_f32_e32 v184, v184
	v_exp_f32_e32 v185, v185
	v_exp_f32_e32 v186, v186
	v_exp_f32_e32 v187, v187
	v_exp_f32_e32 v188, v188
	v_exp_f32_e32 v189, v189
	v_pk_add_f32 v[182:183], v[182:183], 1.0 op_sel_hi:[1,0]
	v_pk_add_f32 v[184:185], v[184:185], 1.0 op_sel_hi:[1,0]
	v_pk_add_f32 v[186:187], v[186:187], 1.0 op_sel_hi:[1,0]
	v_pk_add_f32 v[188:189], v[188:189], 1.0 op_sel_hi:[1,0]
	v_rcp_f32_e32 v182, v182
	v_rcp_f32_e32 v183, v183
	v_rcp_f32_e32 v184, v184
	v_rcp_f32_e32 v185, v185
	v_rcp_f32_e32 v186, v186
	v_rcp_f32_e32 v187, v187
	v_rcp_f32_e32 v188, v188
	v_rcp_f32_e32 v189, v189
	s_nop 0
	v_pk_fma_f32 v[182:183], v[182:183], s[20:21], 0.5 op_sel_hi:[1,0,0]
	v_pk_fma_f32 v[184:185], v[184:185], s[20:21], 0.5 op_sel_hi:[1,0,0]
	v_pk_fma_f32 v[186:187], v[186:187], s[20:21], 0.5 op_sel_hi:[1,0,0]
	v_pk_fma_f32 v[188:189], v[188:189], s[20:21], 0.5 op_sel_hi:[1,0,0]
	v_max_f32_e32 v182, 1.0, v182
	v_max_f32_e32 v183, 1.0, v183
	v_max_f32_e32 v184, 1.0, v184
	v_max_f32_e32 v185, 1.0, v185
	v_max_f32_e32 v186, 1.0, v186
	v_max_f32_e32 v187, 1.0, v187
	v_max_f32_e32 v188, 1.0, v188
	v_max_f32_e32 v189, 1.0, v189
	v_cvt_u32_f32_e32 v190, v182
	v_cvt_u32_f32_e32 v191, v186
	v_cvt_u32_f32_sdwa v190, v183 dst_sel:BYTE_1 dst_unused:UNUSED_PRESERVE src0_sel:DWORD
	v_cvt_u32_f32_sdwa v191, v187 dst_sel:BYTE_1 dst_unused:UNUSED_PRESERVE src0_sel:DWORD
	v_cvt_u32_f32_sdwa v190, v184 dst_sel:BYTE_2 dst_unused:UNUSED_PRESERVE src0_sel:DWORD
	v_cvt_u32_f32_sdwa v191, v188 dst_sel:BYTE_2 dst_unused:UNUSED_PRESERVE src0_sel:DWORD
	v_cvt_u32_f32_sdwa v190, v185 dst_sel:BYTE_3 dst_unused:UNUSED_PRESERVE src0_sel:DWORD
	v_cvt_u32_f32_sdwa v191, v189 dst_sel:BYTE_3 dst_unused:UNUSED_PRESERVE src0_sel:DWORD
	ds_bpermute_b32 v190, v214, v190
	ds_bpermute_b32 v191, v214, v191
	s_waitcnt lgkmcnt(2)
	global_store_dwordx2 v[196:197], v[180:181], off
	v_pk_mul_f32 v[172:173], v[38:39], s[20:21] op_sel:[0,1] op_sel_hi:[1,1]
	v_pk_mul_f32 v[174:175], v[40:41], s[20:21] op_sel:[0,1] op_sel_hi:[1,1]
	v_pk_mul_f32 v[176:177], v[30:31], s[20:21] op_sel:[0,1] op_sel_hi:[1,1]
	v_pk_mul_f32 v[178:179], v[32:33], s[20:21] op_sel:[0,1] op_sel_hi:[1,1]
	v_exp_f32_e32 v172, v172
	v_exp_f32_e32 v173, v173
	v_exp_f32_e32 v174, v174
	v_exp_f32_e32 v175, v175
	v_exp_f32_e32 v176, v176
	v_exp_f32_e32 v177, v177
	v_exp_f32_e32 v178, v178
	v_exp_f32_e32 v179, v179
	v_pk_add_f32 v[172:173], v[172:173], 1.0 op_sel_hi:[1,0]
	v_pk_add_f32 v[174:175], v[174:175], 1.0 op_sel_hi:[1,0]
	v_pk_add_f32 v[176:177], v[176:177], 1.0 op_sel_hi:[1,0]
	v_pk_add_f32 v[178:179], v[178:179], 1.0 op_sel_hi:[1,0]
	v_rcp_f32_e32 v172, v172
	v_rcp_f32_e32 v173, v173
	v_rcp_f32_e32 v174, v174
	v_rcp_f32_e32 v175, v175
	v_rcp_f32_e32 v176, v176
	v_rcp_f32_e32 v177, v177
	v_rcp_f32_e32 v178, v178
	v_rcp_f32_e32 v179, v179
	s_mov_b64 s[0:1], 0xa0000
	v_lshl_add_u64 v[194:195], v[192:193], 0, s[0:1]
	v_pk_fma_f32 v[172:173], v[172:173], s[20:21], 0.5 op_sel_hi:[1,0,0]
	v_pk_fma_f32 v[174:175], v[174:175], s[20:21], 0.5 op_sel_hi:[1,0,0]
	v_pk_fma_f32 v[176:177], v[176:177], s[20:21], 0.5 op_sel_hi:[1,0,0]
	v_pk_fma_f32 v[178:179], v[178:179], s[20:21], 0.5 op_sel_hi:[1,0,0]
	v_max_f32_e32 v172, 1.0, v172
	v_max_f32_e32 v173, 1.0, v173
	v_max_f32_e32 v174, 1.0, v174
	v_max_f32_e32 v175, 1.0, v175
	v_max_f32_e32 v176, 1.0, v176
	v_max_f32_e32 v177, 1.0, v177
	v_max_f32_e32 v178, 1.0, v178
	v_max_f32_e32 v179, 1.0, v179
	v_cvt_u32_f32_e32 v180, v172
	v_cvt_u32_f32_e32 v181, v176
	v_cvt_u32_f32_sdwa v180, v173 dst_sel:BYTE_1 dst_unused:UNUSED_PRESERVE src0_sel:DWORD
	v_cvt_u32_f32_sdwa v181, v177 dst_sel:BYTE_1 dst_unused:UNUSED_PRESERVE src0_sel:DWORD
	v_cvt_u32_f32_sdwa v180, v174 dst_sel:BYTE_2 dst_unused:UNUSED_PRESERVE src0_sel:DWORD
	v_cvt_u32_f32_sdwa v181, v178 dst_sel:BYTE_2 dst_unused:UNUSED_PRESERVE src0_sel:DWORD
	v_cvt_u32_f32_sdwa v180, v175 dst_sel:BYTE_3 dst_unused:UNUSED_PRESERVE src0_sel:DWORD
	v_cvt_u32_f32_sdwa v181, v179 dst_sel:BYTE_3 dst_unused:UNUSED_PRESERVE src0_sel:DWORD
	ds_bpermute_b32 v180, v214, v180
	ds_bpermute_b32 v181, v214, v181
	s_waitcnt lgkmcnt(2)
; __device__ __forceinline__ float sigmoidf_(float x) { return __builtin_amdgcn_rcpf(1.f + __expf(-x)); }
;     __device__ __forceinline__ void operator()(f32x4 (&acc)[2][2][4][2], const pg8::Unit& u, int wr, int wc, int fr, int fq) const {
;     ...
;             for (int ai = 0; ai < 2; ++ai)
; #pragma unroll
;                 for (int m = 0; m < 4; ++m) {
;                     unsigned char* gp = gq + (size_t)(row0 + ai * 128 + m * 16) * 4096 + (u.pn - 28) * 256 + cin;
; #pragma unroll
;                     for (int bj = 0; bj < 2; ++bj) { unsigned w2[2];
; #pragma unroll
;                         for (int n = 0; n < 2; ++n) {
;                             const f32x4 v = acc[ai][bj][m][n];
;                             const unsigned b0 = (unsigned)(sigmoidf_(v[0]) * 255.f + 0.5f), b1 = (unsigned)(sigmoidf_(v[1]) * 255.f + 0.5f),
;                                            b2 = (unsigned)(sigmoidf_(v[2]) * 255.f + 0.5f), b3 = (unsigned)(sigmoidf_(v[3]) * 255.f + 0.5f);
;                             w2[n] = b0 | (b1 << 8) | (b2 << 16) | (b3 << 24);
;                         }
;                         u32x2 o = {w2[0], w2[1]}; *(u32x2*)(gp + bj * 128) = o; }
	global_store_dwordx2 v[196:197], v[190:191], off offset:128
	v_pk_mul_f32 v[182:183], v[18:19], s[20:21] op_sel:[0,1] op_sel_hi:[1,1]
	v_pk_mul_f32 v[184:185], v[20:21], s[20:21] op_sel:[0,1] op_sel_hi:[1,1]
	v_pk_mul_f32 v[186:187], v[10:11], s[20:21] op_sel:[0,1] op_sel_hi:[1,1]
	v_pk_mul_f32 v[188:189], v[12:13], s[20:21] op_sel:[0,1] op_sel_hi:[1,1]
	v_exp_f32_e32 v182, v182
	v_exp_f32_e32 v183, v183
	v_exp_f32_e32 v184, v184
	v_exp_f32_e32 v185, v185
	v_exp_f32_e32 v186, v186
	v_exp_f32_e32 v187, v187
	v_exp_f32_e32 v188, v188
	v_exp_f32_e32 v189, v189
	v_pk_add_f32 v[182:183], v[182:183], 1.0 op_sel_hi:[1,0]
	v_pk_add_f32 v[184:185], v[184:185], 1.0 op_sel_hi:[1,0]
	v_pk_add_f32 v[186:187], v[186:187], 1.0 op_sel_hi:[1,0]
	v_pk_add_f32 v[188:189], v[188:189], 1.0 op_sel_hi:[1,0]
	v_rcp_f32_e32 v182, v182
	v_rcp_f32_e32 v183, v183
	v_rcp_f32_e32 v184, v184
	v_rcp_f32_e32 v185, v185
	v_rcp_f32_e32 v186, v186
	v_rcp_f32_e32 v187, v187
	v_rcp_f32_e32 v188, v188
	v_rcp_f32_e32 v189, v189
	s_nop 0
	v_pk_fma_f32 v[182:183], v[182:183], s[20:21], 0.5 op_sel_hi:[1,0,0]
	v_pk_fma_f32 v[184:185], v[184:185], s[20:21], 0.5 op_sel_hi:[1,0,0]
	v_pk_fma_f32 v[186:187], v[186:187], s[20:21], 0.5 op_sel_hi:[1,0,0]
	v_pk_fma_f32 v[188:189], v[188:189], s[20:21], 0.5 op_sel_hi:[1,0,0]
	v_max_f32_e32 v182, 1.0, v182
	v_max_f32_e32 v183, 1.0, v183
	v_max_f32_e32 v184, 1.0, v184
	v_max_f32_e32 v185, 1.0, v185
	v_max_f32_e32 v186, 1.0, v186
	v_max_f32_e32 v187, 1.0, v187
	v_max_f32_e32 v188, 1.0, v188
	v_max_f32_e32 v189, 1.0, v189
	v_cvt_u32_f32_e32 v190, v182
	v_cvt_u32_f32_e32 v191, v186
	v_cvt_u32_f32_sdwa v190, v183 dst_sel:BYTE_1 dst_unused:UNUSED_PRESERVE src0_sel:DWORD
	v_cvt_u32_f32_sdwa v191, v187 dst_sel:BYTE_1 dst_unused:UNUSED_PRESERVE src0_sel:DWORD
	v_cvt_u32_f32_sdwa v190, v184 dst_sel:BYTE_2 dst_unused:UNUSED_PRESERVE src0_sel:DWORD
	v_cvt_u32_f32_sdwa v191, v188 dst_sel:BYTE_2 dst_unused:UNUSED_PRESERVE src0_sel:DWORD
	v_cvt_u32_f32_sdwa v190, v185 dst_sel:BYTE_3 dst_unused:UNUSED_PRESERVE src0_sel:DWORD
	v_cvt_u32_f32_sdwa v191, v189 dst_sel:BYTE_3 dst_unused:UNUSED_PRESERVE src0_sel:DWORD
	ds_bpermute_b32 v190, v214, v190
	ds_bpermute_b32 v191, v214, v191
	s_waitcnt lgkmcnt(2)
	global_store_dwordx2 v[194:195], v[180:181], off
	v_pk_mul_f32 v[172:173], v[22:23], s[20:21] op_sel:[0,1] op_sel_hi:[1,1]
	v_pk_mul_f32 v[174:175], v[24:25], s[20:21] op_sel:[0,1] op_sel_hi:[1,1]
	v_pk_mul_f32 v[176:177], v[14:15], s[20:21] op_sel:[0,1] op_sel_hi:[1,1]
	v_pk_mul_f32 v[178:179], v[16:17], s[20:21] op_sel:[0,1] op_sel_hi:[1,1]
	v_exp_f32_e32 v172, v172
	v_exp_f32_e32 v173, v173
	v_exp_f32_e32 v174, v174
	v_exp_f32_e32 v175, v175
	v_exp_f32_e32 v176, v176
	v_exp_f32_e32 v177, v177
	v_exp_f32_e32 v178, v178
	v_exp_f32_e32 v179, v179
	v_pk_add_f32 v[172:173], v[172:173], 1.0 op_sel_hi:[1,0]
	v_pk_add_f32 v[174:175], v[174:175], 1.0 op_sel_hi:[1,0]
	v_pk_add_f32 v[176:177], v[176:177], 1.0 op_sel_hi:[1,0]
	v_pk_add_f32 v[178:179], v[178:179], 1.0 op_sel_hi:[1,0]
	v_rcp_f32_e32 v172, v172
	v_rcp_f32_e32 v173, v173
	v_rcp_f32_e32 v174, v174
	v_rcp_f32_e32 v175, v175
	v_rcp_f32_e32 v176, v176
	v_rcp_f32_e32 v177, v177
	v_rcp_f32_e32 v178, v178
	v_rcp_f32_e32 v179, v179
	s_mov_b64 s[0:1], 0xb0000
	v_lshl_add_u64 v[196:197], v[192:193], 0, s[0:1]
	v_pk_fma_f32 v[172:173], v[172:173], s[20:21], 0.5 op_sel_hi:[1,0,0]
	v_pk_fma_f32 v[174:175], v[174:175], s[20:21], 0.5 op_sel_hi:[1,0,0]
	v_pk_fma_f32 v[176:177], v[176:177], s[20:21], 0.5 op_sel_hi:[1,0,0]
	v_pk_fma_f32 v[178:179], v[178:179], s[20:21], 0.5 op_sel_hi:[1,0,0]
	v_max_f32_e32 v172, 1.0, v172
	v_max_f32_e32 v173, 1.0, v173
	v_max_f32_e32 v174, 1.0, v174
	v_max_f32_e32 v175, 1.0, v175
	v_max_f32_e32 v176, 1.0, v176
	v_max_f32_e32 v177, 1.0, v177
	v_max_f32_e32 v178, 1.0, v178
	v_max_f32_e32 v179, 1.0, v179
	v_cvt_u32_f32_e32 v180, v172
	v_cvt_u32_f32_e32 v181, v176
	v_cvt_u32_f32_sdwa v180, v173 dst_sel:BYTE_1 dst_unused:UNUSED_PRESERVE src0_sel:DWORD
	v_cvt_u32_f32_sdwa v181, v177 dst_sel:BYTE_1 dst_unused:UNUSED_PRESERVE src0_sel:DWORD
	v_cvt_u32_f32_sdwa v180, v174 dst_sel:BYTE_2 dst_unused:UNUSED_PRESERVE src0_sel:DWORD
	v_cvt_u32_f32_sdwa v181, v178 dst_sel:BYTE_2 dst_unused:UNUSED_PRESERVE src0_sel:DWORD
	v_cvt_u32_f32_sdwa v180, v175 dst_sel:BYTE_3 dst_unused:UNUSED_PRESERVE src0_sel:DWORD
	v_cvt_u32_f32_sdwa v181, v179 dst_sel:BYTE_3 dst_unused:UNUSED_PRESERVE src0_sel:DWORD
	ds_bpermute_b32 v180, v214, v180
	ds_bpermute_b32 v181, v214, v181
	s_waitcnt lgkmcnt(2)
	global_store_dwordx2 v[194:195], v[190:191], off offset:128
	v_pk_mul_f32 v[182:183], v[6:7], s[20:21] op_sel:[0,1] op_sel_hi:[1,1]
	v_pk_mul_f32 v[184:185], v[8:9], s[20:21] op_sel:[0,1] op_sel_hi:[1,1]
	v_pk_mul_f32 v[186:187], v[2:3], s[20:21] op_sel:[0,1] op_sel_hi:[1,1]
	v_pk_mul_f32 v[188:189], v[4:5], s[20:21] op_sel:[0,1] op_sel_hi:[1,1]
	v_exp_f32_e32 v182, v182
	v_exp_f32_e32 v183, v183
	v_exp_f32_e32 v184, v184
	v_exp_f32_e32 v185, v185
	v_exp_f32_e32 v186, v186
	v_exp_f32_e32 v187, v187
	v_exp_f32_e32 v188, v188
	v_exp_f32_e32 v189, v189
	v_pk_add_f32 v[182:183], v[182:183], 1.0 op_sel_hi:[1,0]
	v_pk_add_f32 v[184:185], v[184:185], 1.0 op_sel_hi:[1,0]
	v_pk_add_f32 v[186:187], v[186:187], 1.0 op_sel_hi:[1,0]
	v_pk_add_f32 v[188:189], v[188:189], 1.0 op_sel_hi:[1,0]
	v_rcp_f32_e32 v182, v182
	v_rcp_f32_e32 v183, v183
	v_rcp_f32_e32 v184, v184
	v_rcp_f32_e32 v185, v185
	v_rcp_f32_e32 v186, v186
	v_rcp_f32_e32 v187, v187
	v_rcp_f32_e32 v188, v188
	v_rcp_f32_e32 v189, v189
	s_nop 0
	v_pk_fma_f32 v[182:183], v[182:183], s[20:21], 0.5 op_sel_hi:[1,0,0]
	v_pk_fma_f32 v[184:185], v[184:185], s[20:21], 0.5 op_sel_hi:[1,0,0]
	v_pk_fma_f32 v[186:187], v[186:187], s[20:21], 0.5 op_sel_hi:[1,0,0]
	v_pk_fma_f32 v[188:189], v[188:189], s[20:21], 0.5 op_sel_hi:[1,0,0]
	v_max_f32_e32 v182, 1.0, v182
	v_max_f32_e32 v183, 1.0, v183
	v_max_f32_e32 v184, 1.0, v184
	v_max_f32_e32 v185, 1.0, v185
	v_max_f32_e32 v186, 1.0, v186
	v_max_f32_e32 v187, 1.0, v187
	v_max_f32_e32 v188, 1.0, v188
	v_max_f32_e32 v189, 1.0, v189
	v_cvt_u32_f32_e32 v190, v182
	v_cvt_u32_f32_e32 v191, v186
	v_cvt_u32_f32_sdwa v190, v183 dst_sel:BYTE_1 dst_unused:UNUSED_PRESERVE src0_sel:DWORD
	v_cvt_u32_f32_sdwa v191, v187 dst_sel:BYTE_1 dst_unused:UNUSED_PRESERVE src0_sel:DWORD
	v_cvt_u32_f32_sdwa v190, v184 dst_sel:BYTE_2 dst_unused:UNUSED_PRESERVE src0_sel:DWORD
	v_cvt_u32_f32_sdwa v191, v188 dst_sel:BYTE_2 dst_unused:UNUSED_PRESERVE src0_sel:DWORD
	v_cvt_u32_f32_sdwa v190, v185 dst_sel:BYTE_3 dst_unused:UNUSED_PRESERVE src0_sel:DWORD
	v_cvt_u32_f32_sdwa v191, v189 dst_sel:BYTE_3 dst_unused:UNUSED_PRESERVE src0_sel:DWORD
	ds_bpermute_b32 v190, v214, v190
	ds_bpermute_b32 v191, v214, v191
	s_waitcnt lgkmcnt(2)
	global_store_dwordx2 v[196:197], v[180:181], off
	s_waitcnt lgkmcnt(0)
	global_store_dwordx2 v[196:197], v[190:191], off offset:128
